# loop-edge edit: K-loop counter/pointer increments and exit compare moved from behind the loop-back barrier to the tail of the last load segment (in-proj, out, ff1, ff2)
# baseline (speedup 1.0000x reference)
.LBB0_565:
	s_add_u32 s8, s6, 0xfff80080
	s_addc_u32 s9, s7, -1
	s_add_i32 s56, 0, 0x10000
	s_cmp_eq_u32 s51, 28
	s_cselect_b32 s11, s28, s9
	s_cselect_b32 s10, s34, s8
	v_add_u32_e32 v2, s56, v193
	s_cselect_b32 s9, s35, s49
	s_cselect_b32 s8, s44, s45
	s_add_i32 s58, 0, 0x14000
	ds_read_b128 v[132:135], v2
	ds_read_b128 v[136:139], v2 offset:1024
	ds_read_b128 v[140:143], v2 offset:2048
	ds_read_b128 v[144:147], v2 offset:3072
	v_add_u32_e32 v2, s58, v193
	ds_read_b128 v[148:151], v2
	ds_read_b128 v[152:155], v2 offset:1024
	ds_read_b128 v[156:159], v2 offset:2048
	ds_read_b128 v[160:163], v2 offset:3072
	v_lshl_add_u64 v[236:237], s[6:7], 0, v[188:189]
	s_add_i32 m0, s16, 0xc000
	ds_read_b128 v[164:167], v207
	ds_read_b128 v[208:211], v207 offset:1024
	ds_read_b128 v[212:215], v207 offset:2048
	ds_read_b128 v[216:219], v207 offset:3072
	ds_read_b128 v[220:223], v207 offset:4096
	ds_read_b128 v[224:227], v207 offset:5120
	ds_read_b128 v[228:231], v207 offset:6144
	ds_read_b128 v[232:235], v207 offset:7168
	global_load_lds_dwordx4 v[236:237], off
	v_lshl_add_u64 v[236:237], s[6:7], 0, v[190:191]
	s_add_i32 m0, s16, 0xe000
	s_nop 0
	global_load_lds_dwordx4 v[236:237], off
	s_waitcnt vmcnt(8)
	s_waitcnt lgkmcnt(0)
	s_barrier
	s_waitcnt lgkmcnt(0)
	v_mfma_f32_16x16x32_bf16 v[128:131], v[132:135], v[164:167], v[128:131]
	v_mfma_f32_16x16x32_bf16 v[124:127], v[140:143], v[164:167], v[124:127]
	v_mfma_f32_16x16x32_bf16 v[112:115], v[132:135], v[212:215], v[112:115]
	v_mfma_f32_16x16x32_bf16 v[108:111], v[140:143], v[212:215], v[108:111]
	v_mfma_f32_16x16x32_bf16 v[96:99], v[132:135], v[220:223], v[96:99]
	v_mfma_f32_16x16x32_bf16 v[92:95], v[140:143], v[220:223], v[92:95]
	v_mfma_f32_16x16x32_bf16 v[80:83], v[132:135], v[228:231], v[80:83]
	v_mfma_f32_16x16x32_bf16 v[76:79], v[140:143], v[228:231], v[76:79]
	v_mfma_f32_16x16x32_bf16 v[128:131], v[136:139], v[208:211], v[128:131]
	v_mfma_f32_16x16x32_bf16 v[124:127], v[144:147], v[208:211], v[124:127]
	v_mfma_f32_16x16x32_bf16 v[112:115], v[136:139], v[216:219], v[112:115]
	v_mfma_f32_16x16x32_bf16 v[108:111], v[144:147], v[216:219], v[108:111]
	v_mfma_f32_16x16x32_bf16 v[96:99], v[136:139], v[224:227], v[96:99]
	v_mfma_f32_16x16x32_bf16 v[92:95], v[144:147], v[224:227], v[92:95]
	v_mfma_f32_16x16x32_bf16 v[80:83], v[136:139], v[232:235], v[80:83]
	v_mfma_f32_16x16x32_bf16 v[76:79], v[144:147], v[232:235], v[76:79]
	v_mfma_f32_16x16x32_bf16 v[120:123], v[148:151], v[164:167], v[120:123]
	v_mfma_f32_16x16x32_bf16 v[116:119], v[156:159], v[164:167], v[116:119]
	v_mfma_f32_16x16x32_bf16 v[104:107], v[148:151], v[212:215], v[104:107]
	v_mfma_f32_16x16x32_bf16 v[100:103], v[156:159], v[212:215], v[100:103]
	v_mfma_f32_16x16x32_bf16 v[88:91], v[148:151], v[220:223], v[88:91]
	v_mfma_f32_16x16x32_bf16 v[84:87], v[156:159], v[220:223], v[84:87]
	v_mfma_f32_16x16x32_bf16 v[72:75], v[148:151], v[228:231], v[72:75]
	v_mfma_f32_16x16x32_bf16 v[68:71], v[156:159], v[228:231], v[68:71]
	v_mfma_f32_16x16x32_bf16 v[120:123], v[152:155], v[208:211], v[120:123]
	v_mfma_f32_16x16x32_bf16 v[116:119], v[160:163], v[208:211], v[116:119]
	v_mfma_f32_16x16x32_bf16 v[104:107], v[152:155], v[216:219], v[104:107]
	v_mfma_f32_16x16x32_bf16 v[100:103], v[160:163], v[216:219], v[100:103]
	v_mfma_f32_16x16x32_bf16 v[88:91], v[152:155], v[224:227], v[88:91]
	v_mfma_f32_16x16x32_bf16 v[84:87], v[160:163], v[224:227], v[84:87]
	v_mfma_f32_16x16x32_bf16 v[72:75], v[152:155], v[232:235], v[72:75]
	v_mfma_f32_16x16x32_bf16 v[68:71], v[160:163], v[232:235], v[68:71]
	s_barrier
	s_add_i32 s56, s56, s15
	v_lshl_add_u64 v[236:237], s[8:9], 0, v[184:185]
	s_mov_b32 m0, s56
	ds_read_b128 v[164:167], v207 offset:16384
	ds_read_b128 v[208:211], v207 offset:17408
	ds_read_b128 v[212:215], v207 offset:18432
	ds_read_b128 v[216:219], v207 offset:19456
	ds_read_b128 v[220:223], v207 offset:20480
	ds_read_b128 v[224:227], v207 offset:21504
	ds_read_b128 v[228:231], v207 offset:22528
	ds_read_b128 v[232:235], v207 offset:23552
	global_load_lds_dwordx4 v[236:237], off
	s_add_i32 m0, s56, 0x2000
	s_add_u32 s56, s8, 0x80000
	v_lshl_add_u64 v[238:239], s[8:9], 0, v[180:181]
	s_addc_u32 s57, s9, 0
	s_add_i32 s58, s58, s15
	global_load_lds_dwordx4 v[238:239], off
	v_lshl_add_u64 v[240:241], s[56:57], 0, v[184:185]
	s_mov_b32 m0, s58
	v_lshl_add_u64 v[242:243], s[10:11], 0, v[182:183]
	global_load_lds_dwordx4 v[240:241], off
	v_lshl_add_u64 v[240:241], s[56:57], 0, v[180:181]
	s_add_i32 m0, s58, 0x2000
	s_nop 0
	global_load_lds_dwordx4 v[240:241], off
	v_lshl_add_u64 v[240:241], s[10:11], 0, v[186:187]
	s_mov_b32 m0, s16
	s_nop 0
	global_load_lds_dwordx4 v[240:241], off
	s_mov_b32 m0, s17
	s_nop 0
	global_load_lds_dwordx4 v[242:243], off
	s_waitcnt vmcnt(8)
	s_waitcnt lgkmcnt(0)
	s_barrier
	s_waitcnt lgkmcnt(0)
	v_mfma_f32_16x16x32_bf16 v[64:67], v[132:135], v[164:167], v[64:67]
	v_mfma_f32_16x16x32_bf16 v[60:63], v[140:143], v[164:167], v[60:63]
	v_mfma_f32_16x16x32_bf16 v[48:51], v[132:135], v[212:215], v[48:51]
	v_mfma_f32_16x16x32_bf16 v[44:47], v[140:143], v[212:215], v[44:47]
	v_mfma_f32_16x16x32_bf16 v[32:35], v[132:135], v[220:223], v[32:35]
	v_mfma_f32_16x16x32_bf16 v[28:31], v[140:143], v[220:223], v[28:31]
	v_mfma_f32_16x16x32_bf16 v[16:19], v[132:135], v[228:231], v[16:19]
	v_mfma_f32_16x16x32_bf16 v[12:15], v[140:143], v[228:231], v[12:15]
	v_mfma_f32_16x16x32_bf16 v[64:67], v[136:139], v[208:211], v[64:67]
	v_mfma_f32_16x16x32_bf16 v[60:63], v[144:147], v[208:211], v[60:63]
	v_mfma_f32_16x16x32_bf16 v[48:51], v[136:139], v[216:219], v[48:51]
	v_mfma_f32_16x16x32_bf16 v[44:47], v[144:147], v[216:219], v[44:47]
	v_mfma_f32_16x16x32_bf16 v[32:35], v[136:139], v[224:227], v[32:35]
	v_mfma_f32_16x16x32_bf16 v[28:31], v[144:147], v[224:227], v[28:31]
	v_mfma_f32_16x16x32_bf16 v[16:19], v[136:139], v[232:235], v[16:19]
	v_mfma_f32_16x16x32_bf16 v[12:15], v[144:147], v[232:235], v[12:15]
	v_mfma_f32_16x16x32_bf16 v[56:59], v[148:151], v[164:167], v[56:59]
	v_mfma_f32_16x16x32_bf16 v[52:55], v[156:159], v[164:167], v[52:55]
	v_mfma_f32_16x16x32_bf16 v[40:43], v[148:151], v[212:215], v[40:43]
	v_mfma_f32_16x16x32_bf16 v[36:39], v[156:159], v[212:215], v[36:39]
	v_mfma_f32_16x16x32_bf16 v[24:27], v[148:151], v[220:223], v[24:27]
	v_mfma_f32_16x16x32_bf16 v[20:23], v[156:159], v[220:223], v[20:23]
	v_mfma_f32_16x16x32_bf16 v[8:11], v[148:151], v[228:231], v[8:11]
	v_mfma_f32_16x16x32_bf16 v[4:7], v[156:159], v[228:231], v[4:7]
	v_mfma_f32_16x16x32_bf16 v[56:59], v[152:155], v[208:211], v[56:59]
	v_mfma_f32_16x16x32_bf16 v[52:55], v[160:163], v[208:211], v[52:55]
	v_mfma_f32_16x16x32_bf16 v[40:43], v[152:155], v[216:219], v[40:43]
	v_mfma_f32_16x16x32_bf16 v[36:39], v[160:163], v[216:219], v[36:39]
	v_mfma_f32_16x16x32_bf16 v[24:27], v[152:155], v[224:227], v[24:27]
	v_mfma_f32_16x16x32_bf16 v[20:23], v[160:163], v[224:227], v[20:23]
	v_mfma_f32_16x16x32_bf16 v[8:11], v[152:155], v[232:235], v[8:11]
	v_mfma_f32_16x16x32_bf16 v[4:7], v[160:163], v[232:235], v[4:7]
	s_barrier
	s_add_i32 s56, 0, 0x18000
	v_add_u32_e32 v2, s56, v193
	s_add_i32 s57, 0, 0x1c000
	ds_read_b128 v[132:135], v2
	ds_read_b128 v[136:139], v2 offset:1024
	ds_read_b128 v[140:143], v2 offset:2048
	ds_read_b128 v[144:147], v2 offset:3072
	v_add_u32_e32 v2, s57, v193
	ds_read_b128 v[148:151], v2
	ds_read_b128 v[152:155], v2 offset:1024
	ds_read_b128 v[156:159], v2 offset:2048
	ds_read_b128 v[160:163], v2 offset:3072
	s_add_u32 s10, s10, 0x80000
	s_addc_u32 s11, s11, 0
	s_mov_b32 m0, s18
	v_lshl_add_u64 v[244:245], s[10:11], 0, v[186:187]
	ds_read_b128 v[164:167], v207 offset:32768
	ds_read_b128 v[208:211], v207 offset:33792
	ds_read_b128 v[212:215], v207 offset:34816
	ds_read_b128 v[216:219], v207 offset:35840
	ds_read_b128 v[220:223], v207 offset:36864
	ds_read_b128 v[224:227], v207 offset:37888
	ds_read_b128 v[228:231], v207 offset:38912
	ds_read_b128 v[232:235], v207 offset:39936
	global_load_lds_dwordx4 v[244:245], off
	v_lshl_add_u64 v[244:245], s[10:11], 0, v[182:183]
	s_mov_b32 m0, s19
	s_nop 0
	global_load_lds_dwordx4 v[244:245], off
	s_waitcnt vmcnt(8)
	s_waitcnt lgkmcnt(0)
	s_barrier
	s_waitcnt lgkmcnt(0)
	v_mfma_f32_16x16x32_bf16 v[128:131], v[132:135], v[164:167], v[128:131]
	v_mfma_f32_16x16x32_bf16 v[124:127], v[140:143], v[164:167], v[124:127]
	v_mfma_f32_16x16x32_bf16 v[112:115], v[132:135], v[212:215], v[112:115]
	v_mfma_f32_16x16x32_bf16 v[108:111], v[140:143], v[212:215], v[108:111]
	v_mfma_f32_16x16x32_bf16 v[96:99], v[132:135], v[220:223], v[96:99]
	v_mfma_f32_16x16x32_bf16 v[92:95], v[140:143], v[220:223], v[92:95]
	v_mfma_f32_16x16x32_bf16 v[80:83], v[132:135], v[228:231], v[80:83]
	v_mfma_f32_16x16x32_bf16 v[76:79], v[140:143], v[228:231], v[76:79]
	v_mfma_f32_16x16x32_bf16 v[128:131], v[136:139], v[208:211], v[128:131]
	v_mfma_f32_16x16x32_bf16 v[124:127], v[144:147], v[208:211], v[124:127]
	v_mfma_f32_16x16x32_bf16 v[112:115], v[136:139], v[216:219], v[112:115]
	v_mfma_f32_16x16x32_bf16 v[108:111], v[144:147], v[216:219], v[108:111]
	v_mfma_f32_16x16x32_bf16 v[96:99], v[136:139], v[224:227], v[96:99]
	v_mfma_f32_16x16x32_bf16 v[92:95], v[144:147], v[224:227], v[92:95]
	v_mfma_f32_16x16x32_bf16 v[80:83], v[136:139], v[232:235], v[80:83]
	v_mfma_f32_16x16x32_bf16 v[76:79], v[144:147], v[232:235], v[76:79]
	v_mfma_f32_16x16x32_bf16 v[120:123], v[148:151], v[164:167], v[120:123]
	v_mfma_f32_16x16x32_bf16 v[116:119], v[156:159], v[164:167], v[116:119]
	v_mfma_f32_16x16x32_bf16 v[104:107], v[148:151], v[212:215], v[104:107]
	v_mfma_f32_16x16x32_bf16 v[100:103], v[156:159], v[212:215], v[100:103]
	v_mfma_f32_16x16x32_bf16 v[88:91], v[148:151], v[220:223], v[88:91]
	v_mfma_f32_16x16x32_bf16 v[84:87], v[156:159], v[220:223], v[84:87]
	v_mfma_f32_16x16x32_bf16 v[72:75], v[148:151], v[228:231], v[72:75]
	v_mfma_f32_16x16x32_bf16 v[68:71], v[156:159], v[228:231], v[68:71]
	v_mfma_f32_16x16x32_bf16 v[120:123], v[152:155], v[208:211], v[120:123]
	v_mfma_f32_16x16x32_bf16 v[116:119], v[160:163], v[208:211], v[116:119]
	v_mfma_f32_16x16x32_bf16 v[104:107], v[152:155], v[216:219], v[104:107]
	v_mfma_f32_16x16x32_bf16 v[100:103], v[160:163], v[216:219], v[100:103]
	v_mfma_f32_16x16x32_bf16 v[88:91], v[152:155], v[224:227], v[88:91]
	v_mfma_f32_16x16x32_bf16 v[84:87], v[160:163], v[224:227], v[84:87]
	v_mfma_f32_16x16x32_bf16 v[72:75], v[152:155], v[232:235], v[72:75]
	v_mfma_f32_16x16x32_bf16 v[68:71], v[160:163], v[232:235], v[68:71]
	s_barrier
	s_add_i32 s10, s56, s15
	v_lshl_add_u64 v[236:237], v[236:237], 0, s[2:3]
	s_mov_b32 m0, s10
	ds_read_b128 v[164:167], v207 offset:49152
	ds_read_b128 v[208:211], v207 offset:50176
	ds_read_b128 v[212:215], v207 offset:51200
	ds_read_b128 v[216:219], v207 offset:52224
	ds_read_b128 v[220:223], v207 offset:53248
	ds_read_b128 v[224:227], v207 offset:54272
	ds_read_b128 v[228:231], v207 offset:55296
	ds_read_b128 v[232:235], v207 offset:56320
	global_load_lds_dwordx4 v[236:237], off
	s_add_i32 m0, s10, 0x2000
	s_add_u32 s8, s8, 0x80080
	v_lshl_add_u64 v[236:237], v[238:239], 0, s[2:3]
	s_addc_u32 s9, s9, 0
	s_add_i32 s10, s57, s15
	global_load_lds_dwordx4 v[236:237], off
	v_lshl_add_u64 v[236:237], s[8:9], 0, v[184:185]
	s_mov_b32 m0, s10
	s_nop 0
	global_load_lds_dwordx4 v[236:237], off
	v_lshl_add_u64 v[236:237], s[8:9], 0, v[180:181]
	s_add_i32 m0, s10, 0x2000
	s_nop 0
	global_load_lds_dwordx4 v[236:237], off
	v_lshl_add_u64 v[236:237], v[240:241], 0, s[2:3]
	s_mov_b32 m0, s20
	s_nop 0
	global_load_lds_dwordx4 v[236:237], off
	v_lshl_add_u64 v[236:237], v[242:243], 0, s[2:3]
	s_mov_b32 m0, s21
	s_nop 0
	global_load_lds_dwordx4 v[236:237], off
	s_add_i32 s51, s51, 2
	s_add_u32 s6, s6, 0x100
	s_addc_u32 s7, s7, 0
	s_add_u32 s45, s45, 0x100
	s_addc_u32 s49, s49, 0
	s_cmp_gt_u32 s51, 29
	s_waitcnt vmcnt(8)
	s_waitcnt lgkmcnt(0)
	s_barrier
	s_waitcnt lgkmcnt(0)
	v_mfma_f32_16x16x32_bf16 v[64:67], v[132:135], v[164:167], v[64:67]
	v_mfma_f32_16x16x32_bf16 v[60:63], v[140:143], v[164:167], v[60:63]
	v_mfma_f32_16x16x32_bf16 v[48:51], v[132:135], v[212:215], v[48:51]
	v_mfma_f32_16x16x32_bf16 v[44:47], v[140:143], v[212:215], v[44:47]
	v_mfma_f32_16x16x32_bf16 v[32:35], v[132:135], v[220:223], v[32:35]
	v_mfma_f32_16x16x32_bf16 v[28:31], v[140:143], v[220:223], v[28:31]
	v_mfma_f32_16x16x32_bf16 v[16:19], v[132:135], v[228:231], v[16:19]
	v_mfma_f32_16x16x32_bf16 v[12:15], v[140:143], v[228:231], v[12:15]
	v_mfma_f32_16x16x32_bf16 v[64:67], v[136:139], v[208:211], v[64:67]
	v_mfma_f32_16x16x32_bf16 v[60:63], v[144:147], v[208:211], v[60:63]
	v_mfma_f32_16x16x32_bf16 v[48:51], v[136:139], v[216:219], v[48:51]
	v_mfma_f32_16x16x32_bf16 v[44:47], v[144:147], v[216:219], v[44:47]
	v_mfma_f32_16x16x32_bf16 v[32:35], v[136:139], v[224:227], v[32:35]
	v_mfma_f32_16x16x32_bf16 v[28:31], v[144:147], v[224:227], v[28:31]
	v_mfma_f32_16x16x32_bf16 v[16:19], v[136:139], v[232:235], v[16:19]
	v_mfma_f32_16x16x32_bf16 v[12:15], v[144:147], v[232:235], v[12:15]
	v_mfma_f32_16x16x32_bf16 v[56:59], v[148:151], v[164:167], v[56:59]
	v_mfma_f32_16x16x32_bf16 v[52:55], v[156:159], v[164:167], v[52:55]
	v_mfma_f32_16x16x32_bf16 v[40:43], v[148:151], v[212:215], v[40:43]
	v_mfma_f32_16x16x32_bf16 v[36:39], v[156:159], v[212:215], v[36:39]
	v_mfma_f32_16x16x32_bf16 v[24:27], v[148:151], v[220:223], v[24:27]
	v_mfma_f32_16x16x32_bf16 v[20:23], v[156:159], v[220:223], v[20:23]
	v_mfma_f32_16x16x32_bf16 v[8:11], v[148:151], v[228:231], v[8:11]
	v_mfma_f32_16x16x32_bf16 v[4:7], v[156:159], v[228:231], v[4:7]
	v_mfma_f32_16x16x32_bf16 v[56:59], v[152:155], v[208:211], v[56:59]
	v_mfma_f32_16x16x32_bf16 v[52:55], v[160:163], v[208:211], v[52:55]
	v_mfma_f32_16x16x32_bf16 v[40:43], v[152:155], v[216:219], v[40:43]
	v_mfma_f32_16x16x32_bf16 v[36:39], v[160:163], v[216:219], v[36:39]
	v_mfma_f32_16x16x32_bf16 v[24:27], v[152:155], v[224:227], v[24:27]
	v_mfma_f32_16x16x32_bf16 v[20:23], v[160:163], v[224:227], v[20:23]
	v_mfma_f32_16x16x32_bf16 v[8:11], v[152:155], v[232:235], v[8:11]
	v_mfma_f32_16x16x32_bf16 v[4:7], v[160:163], v[232:235], v[4:7]
	s_barrier
	s_cbranch_scc0 .LBB0_565
	s_and_b64 vcc, exec, s[46:47]
	s_cbranch_vccz .LBB0_568
	s_barrier

.LBB0_1087:
	s_add_i32 s52, s20, 2
	s_add_u32 s21, s18, 0xfff80080
	s_addc_u32 s24, s19, -1
	s_add_i32 s53, 0, 0x10000
	s_cmp_eq_u32 s9, s20
	s_cselect_b32 s25, s11, s24
	s_cselect_b32 s24, s10, s21
	v_add_u32_e32 v2, s53, v1
	s_cselect_b32 s21, s17, s51
	s_cselect_b32 s20, s16, s15
	s_add_i32 s56, 0, 0x14000
	ds_read_b128 v[146:149], v2
	ds_read_b128 v[150:153], v2 offset:1024
	ds_read_b128 v[154:157], v2 offset:2048
	ds_read_b128 v[158:161], v2 offset:3072
	v_add_u32_e32 v2, s56, v1
	ds_read_b128 v[162:165], v2
	ds_read_b128 v[180:183], v2 offset:1024
	ds_read_b128 v[184:187], v2 offset:2048
	ds_read_b128 v[188:191], v2 offset:3072
	v_lshl_add_u64 v[166:167], s[18:19], 0, v[140:141]
	s_add_i32 m0, s34, 0xc000
	ds_read_b128 v[192:195], v145
	ds_read_b128 v[196:199], v145 offset:1024
	ds_read_b128 v[208:211], v145 offset:2048
	ds_read_b128 v[212:215], v145 offset:3072
	ds_read_b128 v[216:219], v145 offset:4096
	ds_read_b128 v[220:223], v145 offset:5120
	ds_read_b128 v[224:227], v145 offset:6144
	ds_read_b128 v[228:231], v145 offset:7168
	global_load_lds_dwordx4 v[166:167], off
	v_lshl_add_u64 v[166:167], s[18:19], 0, v[142:143]
	s_add_i32 m0, s34, 0xe000
	s_nop 0
	global_load_lds_dwordx4 v[166:167], off
	s_waitcnt vmcnt(8)
	s_waitcnt lgkmcnt(0)
	s_barrier
	s_waitcnt lgkmcnt(0)
	v_mfma_f32_16x16x32_bf16 v[128:131], v[146:149], v[192:195], v[128:131]
	v_mfma_f32_16x16x32_bf16 v[124:127], v[154:157], v[192:195], v[124:127]
	v_mfma_f32_16x16x32_bf16 v[120:123], v[146:149], v[208:211], v[120:123]
	v_mfma_f32_16x16x32_bf16 v[112:115], v[154:157], v[208:211], v[112:115]
	v_mfma_f32_16x16x32_bf16 v[104:107], v[146:149], v[216:219], v[104:107]
	v_mfma_f32_16x16x32_bf16 v[96:99], v[154:157], v[216:219], v[96:99]
	v_mfma_f32_16x16x32_bf16 v[88:91], v[146:149], v[224:227], v[88:91]
	v_mfma_f32_16x16x32_bf16 v[80:83], v[154:157], v[224:227], v[80:83]
	v_mfma_f32_16x16x32_bf16 v[128:131], v[150:153], v[196:199], v[128:131]
	v_mfma_f32_16x16x32_bf16 v[124:127], v[158:161], v[196:199], v[124:127]
	v_mfma_f32_16x16x32_bf16 v[120:123], v[150:153], v[212:215], v[120:123]
	v_mfma_f32_16x16x32_bf16 v[112:115], v[158:161], v[212:215], v[112:115]
	v_mfma_f32_16x16x32_bf16 v[104:107], v[150:153], v[220:223], v[104:107]
	v_mfma_f32_16x16x32_bf16 v[96:99], v[158:161], v[220:223], v[96:99]
	v_mfma_f32_16x16x32_bf16 v[88:91], v[150:153], v[228:231], v[88:91]
	v_mfma_f32_16x16x32_bf16 v[80:83], v[158:161], v[228:231], v[80:83]
	v_mfma_f32_16x16x32_bf16 v[116:119], v[162:165], v[192:195], v[116:119]
	v_mfma_f32_16x16x32_bf16 v[108:111], v[184:187], v[192:195], v[108:111]
	v_mfma_f32_16x16x32_bf16 v[100:103], v[162:165], v[208:211], v[100:103]
	v_mfma_f32_16x16x32_bf16 v[92:95], v[184:187], v[208:211], v[92:95]
	v_mfma_f32_16x16x32_bf16 v[84:87], v[162:165], v[216:219], v[84:87]
	v_mfma_f32_16x16x32_bf16 v[76:79], v[184:187], v[216:219], v[76:79]
	v_mfma_f32_16x16x32_bf16 v[72:75], v[162:165], v[224:227], v[72:75]
	v_mfma_f32_16x16x32_bf16 v[68:71], v[184:187], v[224:227], v[68:71]
	v_mfma_f32_16x16x32_bf16 v[116:119], v[180:183], v[196:199], v[116:119]
	v_mfma_f32_16x16x32_bf16 v[108:111], v[188:191], v[196:199], v[108:111]
	v_mfma_f32_16x16x32_bf16 v[100:103], v[180:183], v[212:215], v[100:103]
	v_mfma_f32_16x16x32_bf16 v[92:95], v[188:191], v[212:215], v[92:95]
	v_mfma_f32_16x16x32_bf16 v[84:87], v[180:183], v[220:223], v[84:87]
	v_mfma_f32_16x16x32_bf16 v[76:79], v[188:191], v[220:223], v[76:79]
	v_mfma_f32_16x16x32_bf16 v[72:75], v[180:183], v[228:231], v[72:75]
	v_mfma_f32_16x16x32_bf16 v[68:71], v[188:191], v[228:231], v[68:71]
	s_barrier
	s_add_i32 s53, s53, s28
	v_lshl_add_u64 v[166:167], s[20:21], 0, v[136:137]
	s_mov_b32 m0, s53
	ds_read_b128 v[192:195], v145 offset:16384
	ds_read_b128 v[196:199], v145 offset:17408
	ds_read_b128 v[208:211], v145 offset:18432
	ds_read_b128 v[212:215], v145 offset:19456
	ds_read_b128 v[216:219], v145 offset:20480
	ds_read_b128 v[220:223], v145 offset:21504
	ds_read_b128 v[224:227], v145 offset:22528
	ds_read_b128 v[228:231], v145 offset:23552
	global_load_lds_dwordx4 v[166:167], off
	s_add_i32 m0, s53, 0x2000
	s_add_u32 s54, s20, 0x80000
	v_lshl_add_u64 v[232:233], s[20:21], 0, v[132:133]
	s_addc_u32 s55, s21, 0
	s_add_i32 s53, s56, s28
	global_load_lds_dwordx4 v[232:233], off
	v_lshl_add_u64 v[234:235], s[54:55], 0, v[136:137]
	s_mov_b32 m0, s53
	v_lshl_add_u64 v[236:237], s[24:25], 0, v[134:135]
	global_load_lds_dwordx4 v[234:235], off
	v_lshl_add_u64 v[234:235], s[54:55], 0, v[132:133]
	s_add_i32 m0, s53, 0x2000
	s_nop 0
	global_load_lds_dwordx4 v[234:235], off
	v_lshl_add_u64 v[234:235], s[24:25], 0, v[138:139]
	s_mov_b32 m0, s34
	s_nop 0
	global_load_lds_dwordx4 v[234:235], off
	s_mov_b32 m0, s35
	s_nop 0
	global_load_lds_dwordx4 v[236:237], off
	s_waitcnt vmcnt(8)
	s_waitcnt lgkmcnt(0)
	s_barrier
	s_waitcnt lgkmcnt(0)
	v_mfma_f32_16x16x32_bf16 v[64:67], v[146:149], v[192:195], v[64:67]
	v_mfma_f32_16x16x32_bf16 v[60:63], v[154:157], v[192:195], v[60:63]
	v_mfma_f32_16x16x32_bf16 v[56:59], v[146:149], v[208:211], v[56:59]
	v_mfma_f32_16x16x32_bf16 v[48:51], v[154:157], v[208:211], v[48:51]
	v_mfma_f32_16x16x32_bf16 v[40:43], v[146:149], v[216:219], v[40:43]
	v_mfma_f32_16x16x32_bf16 v[32:35], v[154:157], v[216:219], v[32:35]
	v_mfma_f32_16x16x32_bf16 v[24:27], v[146:149], v[224:227], v[24:27]
	v_mfma_f32_16x16x32_bf16 v[16:19], v[154:157], v[224:227], v[16:19]
	v_mfma_f32_16x16x32_bf16 v[64:67], v[150:153], v[196:199], v[64:67]
	v_mfma_f32_16x16x32_bf16 v[60:63], v[158:161], v[196:199], v[60:63]
	v_mfma_f32_16x16x32_bf16 v[56:59], v[150:153], v[212:215], v[56:59]
	v_mfma_f32_16x16x32_bf16 v[48:51], v[158:161], v[212:215], v[48:51]
	v_mfma_f32_16x16x32_bf16 v[40:43], v[150:153], v[220:223], v[40:43]
	v_mfma_f32_16x16x32_bf16 v[32:35], v[158:161], v[220:223], v[32:35]
	v_mfma_f32_16x16x32_bf16 v[24:27], v[150:153], v[228:231], v[24:27]
	v_mfma_f32_16x16x32_bf16 v[16:19], v[158:161], v[228:231], v[16:19]
	v_mfma_f32_16x16x32_bf16 v[52:55], v[162:165], v[192:195], v[52:55]
	v_mfma_f32_16x16x32_bf16 v[44:47], v[184:187], v[192:195], v[44:47]
	v_mfma_f32_16x16x32_bf16 v[36:39], v[162:165], v[208:211], v[36:39]
	v_mfma_f32_16x16x32_bf16 v[28:31], v[184:187], v[208:211], v[28:31]
	v_mfma_f32_16x16x32_bf16 v[20:23], v[162:165], v[216:219], v[20:23]
	v_mfma_f32_16x16x32_bf16 v[12:15], v[184:187], v[216:219], v[12:15]
	v_mfma_f32_16x16x32_bf16 v[8:11], v[162:165], v[224:227], v[8:11]
	v_mfma_f32_16x16x32_bf16 v[4:7], v[184:187], v[224:227], v[4:7]
	v_mfma_f32_16x16x32_bf16 v[52:55], v[180:183], v[196:199], v[52:55]
	v_mfma_f32_16x16x32_bf16 v[44:47], v[188:191], v[196:199], v[44:47]
	v_mfma_f32_16x16x32_bf16 v[36:39], v[180:183], v[212:215], v[36:39]
	v_mfma_f32_16x16x32_bf16 v[28:31], v[188:191], v[212:215], v[28:31]
	v_mfma_f32_16x16x32_bf16 v[20:23], v[180:183], v[220:223], v[20:23]
	v_mfma_f32_16x16x32_bf16 v[12:15], v[188:191], v[220:223], v[12:15]
	v_mfma_f32_16x16x32_bf16 v[8:11], v[180:183], v[228:231], v[8:11]
	v_mfma_f32_16x16x32_bf16 v[4:7], v[188:191], v[228:231], v[4:7]
	s_barrier
	s_add_i32 s53, 0, 0x18000
	v_add_u32_e32 v2, s53, v1
	s_add_i32 s54, 0, 0x1c000
	ds_read_b128 v[146:149], v2
	ds_read_b128 v[150:153], v2 offset:1024
	ds_read_b128 v[154:157], v2 offset:2048
	ds_read_b128 v[158:161], v2 offset:3072
	v_add_u32_e32 v2, s54, v1
	ds_read_b128 v[162:165], v2
	ds_read_b128 v[180:183], v2 offset:1024
	ds_read_b128 v[184:187], v2 offset:2048
	ds_read_b128 v[188:191], v2 offset:3072
	s_add_u32 s24, s24, 0x80000
	s_addc_u32 s25, s25, 0
	s_mov_b32 m0, s40
	v_lshl_add_u64 v[238:239], s[24:25], 0, v[138:139]
	ds_read_b128 v[192:195], v145 offset:32768
	ds_read_b128 v[196:199], v145 offset:33792
	ds_read_b128 v[208:211], v145 offset:34816
	ds_read_b128 v[212:215], v145 offset:35840
	ds_read_b128 v[216:219], v145 offset:36864
	ds_read_b128 v[220:223], v145 offset:37888
	ds_read_b128 v[224:227], v145 offset:38912
	ds_read_b128 v[228:231], v145 offset:39936
	global_load_lds_dwordx4 v[238:239], off
	v_lshl_add_u64 v[238:239], s[24:25], 0, v[134:135]
	s_mov_b32 m0, s41
	s_nop 0
	global_load_lds_dwordx4 v[238:239], off
	s_waitcnt vmcnt(8)
	s_waitcnt lgkmcnt(0)
	s_barrier
	s_waitcnt lgkmcnt(0)
	v_mfma_f32_16x16x32_bf16 v[128:131], v[146:149], v[192:195], v[128:131]
	v_mfma_f32_16x16x32_bf16 v[124:127], v[154:157], v[192:195], v[124:127]
	v_mfma_f32_16x16x32_bf16 v[120:123], v[146:149], v[208:211], v[120:123]
	v_mfma_f32_16x16x32_bf16 v[112:115], v[154:157], v[208:211], v[112:115]
	v_mfma_f32_16x16x32_bf16 v[104:107], v[146:149], v[216:219], v[104:107]
	v_mfma_f32_16x16x32_bf16 v[96:99], v[154:157], v[216:219], v[96:99]
	v_mfma_f32_16x16x32_bf16 v[88:91], v[146:149], v[224:227], v[88:91]
	v_mfma_f32_16x16x32_bf16 v[80:83], v[154:157], v[224:227], v[80:83]
	v_mfma_f32_16x16x32_bf16 v[128:131], v[150:153], v[196:199], v[128:131]
	v_mfma_f32_16x16x32_bf16 v[124:127], v[158:161], v[196:199], v[124:127]
	v_mfma_f32_16x16x32_bf16 v[120:123], v[150:153], v[212:215], v[120:123]
	v_mfma_f32_16x16x32_bf16 v[112:115], v[158:161], v[212:215], v[112:115]
	v_mfma_f32_16x16x32_bf16 v[104:107], v[150:153], v[220:223], v[104:107]
	v_mfma_f32_16x16x32_bf16 v[96:99], v[158:161], v[220:223], v[96:99]
	v_mfma_f32_16x16x32_bf16 v[88:91], v[150:153], v[228:231], v[88:91]
	v_mfma_f32_16x16x32_bf16 v[80:83], v[158:161], v[228:231], v[80:83]
	v_mfma_f32_16x16x32_bf16 v[116:119], v[162:165], v[192:195], v[116:119]
	v_mfma_f32_16x16x32_bf16 v[108:111], v[184:187], v[192:195], v[108:111]
	v_mfma_f32_16x16x32_bf16 v[100:103], v[162:165], v[208:211], v[100:103]
	v_mfma_f32_16x16x32_bf16 v[92:95], v[184:187], v[208:211], v[92:95]
	v_mfma_f32_16x16x32_bf16 v[84:87], v[162:165], v[216:219], v[84:87]
	v_mfma_f32_16x16x32_bf16 v[76:79], v[184:187], v[216:219], v[76:79]
	v_mfma_f32_16x16x32_bf16 v[72:75], v[162:165], v[224:227], v[72:75]
	v_mfma_f32_16x16x32_bf16 v[68:71], v[184:187], v[224:227], v[68:71]
	v_mfma_f32_16x16x32_bf16 v[116:119], v[180:183], v[196:199], v[116:119]
	v_mfma_f32_16x16x32_bf16 v[108:111], v[188:191], v[196:199], v[108:111]
	v_mfma_f32_16x16x32_bf16 v[100:103], v[180:183], v[212:215], v[100:103]
	v_mfma_f32_16x16x32_bf16 v[92:95], v[188:191], v[212:215], v[92:95]
	v_mfma_f32_16x16x32_bf16 v[84:87], v[180:183], v[220:223], v[84:87]
	v_mfma_f32_16x16x32_bf16 v[76:79], v[188:191], v[220:223], v[76:79]
	v_mfma_f32_16x16x32_bf16 v[72:75], v[180:183], v[228:231], v[72:75]
	v_mfma_f32_16x16x32_bf16 v[68:71], v[188:191], v[228:231], v[68:71]
	s_barrier
	s_add_i32 s24, s53, s28
	v_lshl_add_u64 v[166:167], v[166:167], 0, s[2:3]
	s_mov_b32 m0, s24
	ds_read_b128 v[192:195], v145 offset:49152
	ds_read_b128 v[196:199], v145 offset:50176
	ds_read_b128 v[208:211], v145 offset:51200
	ds_read_b128 v[212:215], v145 offset:52224
	ds_read_b128 v[216:219], v145 offset:53248
	ds_read_b128 v[220:223], v145 offset:54272
	ds_read_b128 v[224:227], v145 offset:55296
	ds_read_b128 v[228:231], v145 offset:56320
	global_load_lds_dwordx4 v[166:167], off
	s_add_i32 m0, s24, 0x2000
	s_add_u32 s20, s20, 0x80080
	v_lshl_add_u64 v[166:167], v[232:233], 0, s[2:3]
	s_addc_u32 s21, s21, 0
	s_add_i32 s24, s54, s28
	global_load_lds_dwordx4 v[166:167], off
	v_lshl_add_u64 v[166:167], s[20:21], 0, v[136:137]
	s_mov_b32 m0, s24
	s_nop 0
	global_load_lds_dwordx4 v[166:167], off
	v_lshl_add_u64 v[166:167], s[20:21], 0, v[132:133]
	s_add_i32 m0, s24, 0x2000
	s_nop 0
	global_load_lds_dwordx4 v[166:167], off
	v_lshl_add_u64 v[166:167], v[234:235], 0, s[2:3]
	s_mov_b32 m0, s42
	s_nop 0
	global_load_lds_dwordx4 v[166:167], off
	v_lshl_add_u64 v[166:167], v[236:237], 0, s[2:3]
	s_mov_b32 m0, s43
	s_nop 0
	global_load_lds_dwordx4 v[166:167], off
	s_add_u32 s18, s18, 0x100
	s_addc_u32 s19, s19, 0
	s_add_u32 s15, s15, 0x100
	s_addc_u32 s51, s51, 0
	s_cmp_ge_u32 s52, s47
	s_mov_b32 s20, s52
	s_waitcnt vmcnt(8)
	s_waitcnt lgkmcnt(0)
	s_barrier
	s_waitcnt lgkmcnt(0)
	v_mfma_f32_16x16x32_bf16 v[64:67], v[146:149], v[192:195], v[64:67]
	v_mfma_f32_16x16x32_bf16 v[60:63], v[154:157], v[192:195], v[60:63]
	v_mfma_f32_16x16x32_bf16 v[56:59], v[146:149], v[208:211], v[56:59]
	v_mfma_f32_16x16x32_bf16 v[48:51], v[154:157], v[208:211], v[48:51]
	v_mfma_f32_16x16x32_bf16 v[40:43], v[146:149], v[216:219], v[40:43]
	v_mfma_f32_16x16x32_bf16 v[32:35], v[154:157], v[216:219], v[32:35]
	v_mfma_f32_16x16x32_bf16 v[24:27], v[146:149], v[224:227], v[24:27]
	v_mfma_f32_16x16x32_bf16 v[16:19], v[154:157], v[224:227], v[16:19]
	v_mfma_f32_16x16x32_bf16 v[64:67], v[150:153], v[196:199], v[64:67]
	v_mfma_f32_16x16x32_bf16 v[60:63], v[158:161], v[196:199], v[60:63]
	v_mfma_f32_16x16x32_bf16 v[56:59], v[150:153], v[212:215], v[56:59]
	v_mfma_f32_16x16x32_bf16 v[48:51], v[158:161], v[212:215], v[48:51]
	v_mfma_f32_16x16x32_bf16 v[40:43], v[150:153], v[220:223], v[40:43]
	v_mfma_f32_16x16x32_bf16 v[32:35], v[158:161], v[220:223], v[32:35]
	v_mfma_f32_16x16x32_bf16 v[24:27], v[150:153], v[228:231], v[24:27]
	v_mfma_f32_16x16x32_bf16 v[16:19], v[158:161], v[228:231], v[16:19]
	v_mfma_f32_16x16x32_bf16 v[52:55], v[162:165], v[192:195], v[52:55]
	v_mfma_f32_16x16x32_bf16 v[44:47], v[184:187], v[192:195], v[44:47]
	v_mfma_f32_16x16x32_bf16 v[36:39], v[162:165], v[208:211], v[36:39]
	v_mfma_f32_16x16x32_bf16 v[28:31], v[184:187], v[208:211], v[28:31]
	v_mfma_f32_16x16x32_bf16 v[20:23], v[162:165], v[216:219], v[20:23]
	v_mfma_f32_16x16x32_bf16 v[12:15], v[184:187], v[216:219], v[12:15]
	v_mfma_f32_16x16x32_bf16 v[8:11], v[162:165], v[224:227], v[8:11]
	v_mfma_f32_16x16x32_bf16 v[4:7], v[184:187], v[224:227], v[4:7]
	v_mfma_f32_16x16x32_bf16 v[52:55], v[180:183], v[196:199], v[52:55]
	v_mfma_f32_16x16x32_bf16 v[44:47], v[188:191], v[196:199], v[44:47]
	v_mfma_f32_16x16x32_bf16 v[36:39], v[180:183], v[212:215], v[36:39]
	v_mfma_f32_16x16x32_bf16 v[28:31], v[188:191], v[212:215], v[28:31]
	v_mfma_f32_16x16x32_bf16 v[20:23], v[180:183], v[220:223], v[20:23]
	v_mfma_f32_16x16x32_bf16 v[12:15], v[188:191], v[220:223], v[12:15]
	v_mfma_f32_16x16x32_bf16 v[8:11], v[180:183], v[228:231], v[8:11]
	v_mfma_f32_16x16x32_bf16 v[4:7], v[188:191], v[228:231], v[4:7]
	s_barrier
	s_cbranch_scc0 .LBB0_1087
	s_and_b64 vcc, exec, s[6:7]
	s_cbranch_vccz .LBB0_1090
	s_barrier

.LBB0_1222:
	s_add_u32 s20, s18, 0xfff80080
	s_addc_u32 s21, s19, -1
	s_add_i32 s54, 0, 0x10000
	s_cmp_eq_u32 s53, 28
	s_cselect_b32 s25, s13, s21
	s_cselect_b32 s24, s49, s20
	v_add_u32_e32 v142, s54, v144
	s_cselect_b32 s21, s11, s52
	s_cselect_b32 s20, s50, s51
	s_add_i32 s56, 0, 0x14000
	ds_read_b128 v[148:151], v142
	ds_read_b128 v[152:155], v142 offset:1024
	ds_read_b128 v[156:159], v142 offset:2048
	ds_read_b128 v[160:163], v142 offset:3072
	v_add_u32_e32 v142, s56, v144
	ds_read_b128 v[164:167], v142
	ds_read_b128 v[180:183], v142 offset:1024
	ds_read_b128 v[184:187], v142 offset:2048
	ds_read_b128 v[188:191], v142 offset:3072
	v_lshl_add_u64 v[142:143], s[18:19], 0, v[138:139]
	s_add_i32 m0, s34, 0xc000
	ds_read_b128 v[192:195], v146
	ds_read_b128 v[196:199], v146 offset:1024
	ds_read_b128 v[208:211], v146 offset:2048
	ds_read_b128 v[212:215], v146 offset:3072
	ds_read_b128 v[216:219], v146 offset:4096
	ds_read_b128 v[220:223], v146 offset:5120
	ds_read_b128 v[224:227], v146 offset:6144
	ds_read_b128 v[228:231], v146 offset:7168
	global_load_lds_dwordx4 v[142:143], off
	v_lshl_add_u64 v[142:143], s[18:19], 0, v[140:141]
	s_add_i32 m0, s34, 0xe000
	s_nop 0
	global_load_lds_dwordx4 v[142:143], off
	s_waitcnt vmcnt(8)
	s_waitcnt lgkmcnt(0)
	s_barrier
	s_waitcnt lgkmcnt(0)
	v_mfma_f32_16x16x32_bf16 v[128:131], v[148:151], v[192:195], v[128:131]
	v_mfma_f32_16x16x32_bf16 v[124:127], v[156:159], v[192:195], v[124:127]
	v_mfma_f32_16x16x32_bf16 v[112:115], v[148:151], v[208:211], v[112:115]
	v_mfma_f32_16x16x32_bf16 v[108:111], v[156:159], v[208:211], v[108:111]
	v_mfma_f32_16x16x32_bf16 v[96:99], v[148:151], v[216:219], v[96:99]
	v_mfma_f32_16x16x32_bf16 v[92:95], v[156:159], v[216:219], v[92:95]
	v_mfma_f32_16x16x32_bf16 v[80:83], v[148:151], v[224:227], v[80:83]
	v_mfma_f32_16x16x32_bf16 v[76:79], v[156:159], v[224:227], v[76:79]
	v_mfma_f32_16x16x32_bf16 v[128:131], v[152:155], v[196:199], v[128:131]
	v_mfma_f32_16x16x32_bf16 v[124:127], v[160:163], v[196:199], v[124:127]
	v_mfma_f32_16x16x32_bf16 v[112:115], v[152:155], v[212:215], v[112:115]
	v_mfma_f32_16x16x32_bf16 v[108:111], v[160:163], v[212:215], v[108:111]
	v_mfma_f32_16x16x32_bf16 v[96:99], v[152:155], v[220:223], v[96:99]
	v_mfma_f32_16x16x32_bf16 v[92:95], v[160:163], v[220:223], v[92:95]
	v_mfma_f32_16x16x32_bf16 v[80:83], v[152:155], v[228:231], v[80:83]
	v_mfma_f32_16x16x32_bf16 v[76:79], v[160:163], v[228:231], v[76:79]
	v_mfma_f32_16x16x32_bf16 v[120:123], v[164:167], v[192:195], v[120:123]
	v_mfma_f32_16x16x32_bf16 v[116:119], v[184:187], v[192:195], v[116:119]
	v_mfma_f32_16x16x32_bf16 v[104:107], v[164:167], v[208:211], v[104:107]
	v_mfma_f32_16x16x32_bf16 v[100:103], v[184:187], v[208:211], v[100:103]
	v_mfma_f32_16x16x32_bf16 v[88:91], v[164:167], v[216:219], v[88:91]
	v_mfma_f32_16x16x32_bf16 v[84:87], v[184:187], v[216:219], v[84:87]
	v_mfma_f32_16x16x32_bf16 v[72:75], v[164:167], v[224:227], v[72:75]
	v_mfma_f32_16x16x32_bf16 v[68:71], v[184:187], v[224:227], v[68:71]
	v_mfma_f32_16x16x32_bf16 v[120:123], v[180:183], v[196:199], v[120:123]
	v_mfma_f32_16x16x32_bf16 v[116:119], v[188:191], v[196:199], v[116:119]
	v_mfma_f32_16x16x32_bf16 v[104:107], v[180:183], v[212:215], v[104:107]
	v_mfma_f32_16x16x32_bf16 v[100:103], v[188:191], v[212:215], v[100:103]
	v_mfma_f32_16x16x32_bf16 v[88:91], v[180:183], v[220:223], v[88:91]
	v_mfma_f32_16x16x32_bf16 v[84:87], v[188:191], v[220:223], v[84:87]
	v_mfma_f32_16x16x32_bf16 v[72:75], v[180:183], v[228:231], v[72:75]
	v_mfma_f32_16x16x32_bf16 v[68:71], v[188:191], v[228:231], v[68:71]
	s_barrier
	s_add_i32 s54, s54, s28
	v_lshl_add_u64 v[142:143], s[20:21], 0, v[2:3]
	s_mov_b32 m0, s54
	ds_read_b128 v[192:195], v146 offset:16384
	ds_read_b128 v[196:199], v146 offset:17408
	ds_read_b128 v[208:211], v146 offset:18432
	ds_read_b128 v[212:215], v146 offset:19456
	ds_read_b128 v[216:219], v146 offset:20480
	ds_read_b128 v[220:223], v146 offset:21504
	ds_read_b128 v[224:227], v146 offset:22528
	ds_read_b128 v[228:231], v146 offset:23552
	global_load_lds_dwordx4 v[142:143], off
	s_add_i32 m0, s54, 0x2000
	s_add_u32 s54, s20, 0x80000
	v_lshl_add_u64 v[232:233], s[20:21], 0, v[132:133]
	s_addc_u32 s55, s21, 0
	s_add_i32 s56, s56, s28
	global_load_lds_dwordx4 v[232:233], off
	v_lshl_add_u64 v[234:235], s[54:55], 0, v[2:3]
	s_mov_b32 m0, s56
	v_lshl_add_u64 v[236:237], s[24:25], 0, v[134:135]
	global_load_lds_dwordx4 v[234:235], off
	v_lshl_add_u64 v[234:235], s[54:55], 0, v[132:133]
	s_add_i32 m0, s56, 0x2000
	s_nop 0
	global_load_lds_dwordx4 v[234:235], off
	v_lshl_add_u64 v[234:235], s[24:25], 0, v[136:137]
	s_mov_b32 m0, s34
	s_nop 0
	global_load_lds_dwordx4 v[234:235], off
	s_mov_b32 m0, s35
	s_nop 0
	global_load_lds_dwordx4 v[236:237], off
	s_waitcnt vmcnt(8)
	s_waitcnt lgkmcnt(0)
	s_barrier
	s_waitcnt lgkmcnt(0)
	v_mfma_f32_16x16x32_bf16 v[64:67], v[148:151], v[192:195], v[64:67]
	v_mfma_f32_16x16x32_bf16 v[60:63], v[156:159], v[192:195], v[60:63]
	v_mfma_f32_16x16x32_bf16 v[48:51], v[148:151], v[208:211], v[48:51]
	v_mfma_f32_16x16x32_bf16 v[44:47], v[156:159], v[208:211], v[44:47]
	v_mfma_f32_16x16x32_bf16 v[32:35], v[148:151], v[216:219], v[32:35]
	v_mfma_f32_16x16x32_bf16 v[28:31], v[156:159], v[216:219], v[28:31]
	v_mfma_f32_16x16x32_bf16 v[16:19], v[148:151], v[224:227], v[16:19]
	v_mfma_f32_16x16x32_bf16 v[12:15], v[156:159], v[224:227], v[12:15]
	v_mfma_f32_16x16x32_bf16 v[64:67], v[152:155], v[196:199], v[64:67]
	v_mfma_f32_16x16x32_bf16 v[60:63], v[160:163], v[196:199], v[60:63]
	v_mfma_f32_16x16x32_bf16 v[48:51], v[152:155], v[212:215], v[48:51]
	v_mfma_f32_16x16x32_bf16 v[44:47], v[160:163], v[212:215], v[44:47]
	v_mfma_f32_16x16x32_bf16 v[32:35], v[152:155], v[220:223], v[32:35]
	v_mfma_f32_16x16x32_bf16 v[28:31], v[160:163], v[220:223], v[28:31]
	v_mfma_f32_16x16x32_bf16 v[16:19], v[152:155], v[228:231], v[16:19]
	v_mfma_f32_16x16x32_bf16 v[12:15], v[160:163], v[228:231], v[12:15]
	v_mfma_f32_16x16x32_bf16 v[56:59], v[164:167], v[192:195], v[56:59]
	v_mfma_f32_16x16x32_bf16 v[52:55], v[184:187], v[192:195], v[52:55]
	v_mfma_f32_16x16x32_bf16 v[40:43], v[164:167], v[208:211], v[40:43]
	v_mfma_f32_16x16x32_bf16 v[36:39], v[184:187], v[208:211], v[36:39]
	v_mfma_f32_16x16x32_bf16 v[24:27], v[164:167], v[216:219], v[24:27]
	v_mfma_f32_16x16x32_bf16 v[20:23], v[184:187], v[216:219], v[20:23]
	v_mfma_f32_16x16x32_bf16 v[8:11], v[164:167], v[224:227], v[8:11]
	v_mfma_f32_16x16x32_bf16 v[4:7], v[184:187], v[224:227], v[4:7]
	v_mfma_f32_16x16x32_bf16 v[56:59], v[180:183], v[196:199], v[56:59]
	v_mfma_f32_16x16x32_bf16 v[52:55], v[188:191], v[196:199], v[52:55]
	v_mfma_f32_16x16x32_bf16 v[40:43], v[180:183], v[212:215], v[40:43]
	v_mfma_f32_16x16x32_bf16 v[36:39], v[188:191], v[212:215], v[36:39]
	v_mfma_f32_16x16x32_bf16 v[24:27], v[180:183], v[220:223], v[24:27]
	v_mfma_f32_16x16x32_bf16 v[20:23], v[188:191], v[220:223], v[20:23]
	v_mfma_f32_16x16x32_bf16 v[8:11], v[180:183], v[228:231], v[8:11]
	v_mfma_f32_16x16x32_bf16 v[4:7], v[188:191], v[228:231], v[4:7]
	s_barrier
	s_add_i32 s54, 0, 0x18000
	v_add_u32_e32 v147, s54, v144
	s_add_i32 s55, 0, 0x1c000
	ds_read_b128 v[148:151], v147
	ds_read_b128 v[152:155], v147 offset:1024
	ds_read_b128 v[156:159], v147 offset:2048
	ds_read_b128 v[160:163], v147 offset:3072
	v_add_u32_e32 v147, s55, v144
	ds_read_b128 v[164:167], v147
	ds_read_b128 v[180:183], v147 offset:1024
	ds_read_b128 v[184:187], v147 offset:2048
	ds_read_b128 v[188:191], v147 offset:3072
	s_add_u32 s24, s24, 0x80000
	s_addc_u32 s25, s25, 0
	s_mov_b32 m0, s42
	v_lshl_add_u64 v[238:239], s[24:25], 0, v[136:137]
	ds_read_b128 v[192:195], v146 offset:32768
	ds_read_b128 v[196:199], v146 offset:33792
	ds_read_b128 v[208:211], v146 offset:34816
	ds_read_b128 v[212:215], v146 offset:35840
	ds_read_b128 v[216:219], v146 offset:36864
	ds_read_b128 v[220:223], v146 offset:37888
	ds_read_b128 v[224:227], v146 offset:38912
	ds_read_b128 v[228:231], v146 offset:39936
	global_load_lds_dwordx4 v[238:239], off
	v_lshl_add_u64 v[238:239], s[24:25], 0, v[134:135]
	s_mov_b32 m0, s43
	s_nop 0
	global_load_lds_dwordx4 v[238:239], off
	s_waitcnt vmcnt(8)
	s_waitcnt lgkmcnt(0)
	s_barrier
	s_waitcnt lgkmcnt(0)
	v_mfma_f32_16x16x32_bf16 v[128:131], v[148:151], v[192:195], v[128:131]
	v_mfma_f32_16x16x32_bf16 v[124:127], v[156:159], v[192:195], v[124:127]
	v_mfma_f32_16x16x32_bf16 v[112:115], v[148:151], v[208:211], v[112:115]
	v_mfma_f32_16x16x32_bf16 v[108:111], v[156:159], v[208:211], v[108:111]
	v_mfma_f32_16x16x32_bf16 v[96:99], v[148:151], v[216:219], v[96:99]
	v_mfma_f32_16x16x32_bf16 v[92:95], v[156:159], v[216:219], v[92:95]
	v_mfma_f32_16x16x32_bf16 v[80:83], v[148:151], v[224:227], v[80:83]
	v_mfma_f32_16x16x32_bf16 v[76:79], v[156:159], v[224:227], v[76:79]
	v_mfma_f32_16x16x32_bf16 v[128:131], v[152:155], v[196:199], v[128:131]
	v_mfma_f32_16x16x32_bf16 v[124:127], v[160:163], v[196:199], v[124:127]
	v_mfma_f32_16x16x32_bf16 v[112:115], v[152:155], v[212:215], v[112:115]
	v_mfma_f32_16x16x32_bf16 v[108:111], v[160:163], v[212:215], v[108:111]
	v_mfma_f32_16x16x32_bf16 v[96:99], v[152:155], v[220:223], v[96:99]
	v_mfma_f32_16x16x32_bf16 v[92:95], v[160:163], v[220:223], v[92:95]
	v_mfma_f32_16x16x32_bf16 v[80:83], v[152:155], v[228:231], v[80:83]
	v_mfma_f32_16x16x32_bf16 v[76:79], v[160:163], v[228:231], v[76:79]
	v_mfma_f32_16x16x32_bf16 v[120:123], v[164:167], v[192:195], v[120:123]
	v_mfma_f32_16x16x32_bf16 v[116:119], v[184:187], v[192:195], v[116:119]
	v_mfma_f32_16x16x32_bf16 v[104:107], v[164:167], v[208:211], v[104:107]
	v_mfma_f32_16x16x32_bf16 v[100:103], v[184:187], v[208:211], v[100:103]
	v_mfma_f32_16x16x32_bf16 v[88:91], v[164:167], v[216:219], v[88:91]
	v_mfma_f32_16x16x32_bf16 v[84:87], v[184:187], v[216:219], v[84:87]
	v_mfma_f32_16x16x32_bf16 v[72:75], v[164:167], v[224:227], v[72:75]
	v_mfma_f32_16x16x32_bf16 v[68:71], v[184:187], v[224:227], v[68:71]
	v_mfma_f32_16x16x32_bf16 v[120:123], v[180:183], v[196:199], v[120:123]
	v_mfma_f32_16x16x32_bf16 v[116:119], v[188:191], v[196:199], v[116:119]
	v_mfma_f32_16x16x32_bf16 v[104:107], v[180:183], v[212:215], v[104:107]
	v_mfma_f32_16x16x32_bf16 v[100:103], v[188:191], v[212:215], v[100:103]
	v_mfma_f32_16x16x32_bf16 v[88:91], v[180:183], v[220:223], v[88:91]
	v_mfma_f32_16x16x32_bf16 v[84:87], v[188:191], v[220:223], v[84:87]
	v_mfma_f32_16x16x32_bf16 v[72:75], v[180:183], v[228:231], v[72:75]
	v_mfma_f32_16x16x32_bf16 v[68:71], v[188:191], v[228:231], v[68:71]
	s_barrier
	s_add_i32 s24, s54, s28
	v_lshl_add_u64 v[142:143], v[142:143], 0, s[2:3]
	s_mov_b32 m0, s24
	ds_read_b128 v[192:195], v146 offset:49152
	ds_read_b128 v[196:199], v146 offset:50176
	ds_read_b128 v[208:211], v146 offset:51200
	ds_read_b128 v[212:215], v146 offset:52224
	ds_read_b128 v[216:219], v146 offset:53248
	ds_read_b128 v[220:223], v146 offset:54272
	ds_read_b128 v[224:227], v146 offset:55296
	ds_read_b128 v[228:231], v146 offset:56320
	global_load_lds_dwordx4 v[142:143], off
	s_add_i32 m0, s24, 0x2000
	s_add_u32 s20, s20, 0x80080
	v_lshl_add_u64 v[142:143], v[232:233], 0, s[2:3]
	s_addc_u32 s21, s21, 0
	s_add_i32 s24, s55, s28
	global_load_lds_dwordx4 v[142:143], off
	v_lshl_add_u64 v[142:143], s[20:21], 0, v[2:3]
	s_mov_b32 m0, s24
	s_nop 0
	global_load_lds_dwordx4 v[142:143], off
	v_lshl_add_u64 v[142:143], s[20:21], 0, v[132:133]
	s_add_i32 m0, s24, 0x2000
	s_nop 0
	global_load_lds_dwordx4 v[142:143], off
	v_lshl_add_u64 v[142:143], v[234:235], 0, s[2:3]
	s_mov_b32 m0, s44
	s_nop 0
	global_load_lds_dwordx4 v[142:143], off
	v_lshl_add_u64 v[142:143], v[236:237], 0, s[2:3]
	s_mov_b32 m0, s45
	s_nop 0
	global_load_lds_dwordx4 v[142:143], off
	s_add_i32 s53, s53, 2
	s_add_u32 s18, s18, 0x100
	s_addc_u32 s19, s19, 0
	s_add_u32 s51, s51, 0x100
	s_addc_u32 s52, s52, 0
	s_cmp_gt_u32 s53, 29
	s_waitcnt vmcnt(8)
	s_waitcnt lgkmcnt(0)
	s_barrier
	s_waitcnt lgkmcnt(0)
	v_mfma_f32_16x16x32_bf16 v[64:67], v[148:151], v[192:195], v[64:67]
	v_mfma_f32_16x16x32_bf16 v[60:63], v[156:159], v[192:195], v[60:63]
	v_mfma_f32_16x16x32_bf16 v[48:51], v[148:151], v[208:211], v[48:51]
	v_mfma_f32_16x16x32_bf16 v[44:47], v[156:159], v[208:211], v[44:47]
	v_mfma_f32_16x16x32_bf16 v[32:35], v[148:151], v[216:219], v[32:35]
	v_mfma_f32_16x16x32_bf16 v[28:31], v[156:159], v[216:219], v[28:31]
	v_mfma_f32_16x16x32_bf16 v[16:19], v[148:151], v[224:227], v[16:19]
	v_mfma_f32_16x16x32_bf16 v[12:15], v[156:159], v[224:227], v[12:15]
	v_mfma_f32_16x16x32_bf16 v[64:67], v[152:155], v[196:199], v[64:67]
	v_mfma_f32_16x16x32_bf16 v[60:63], v[160:163], v[196:199], v[60:63]
	v_mfma_f32_16x16x32_bf16 v[48:51], v[152:155], v[212:215], v[48:51]
	v_mfma_f32_16x16x32_bf16 v[44:47], v[160:163], v[212:215], v[44:47]
	v_mfma_f32_16x16x32_bf16 v[32:35], v[152:155], v[220:223], v[32:35]
	v_mfma_f32_16x16x32_bf16 v[28:31], v[160:163], v[220:223], v[28:31]
	v_mfma_f32_16x16x32_bf16 v[16:19], v[152:155], v[228:231], v[16:19]
	v_mfma_f32_16x16x32_bf16 v[12:15], v[160:163], v[228:231], v[12:15]
	v_mfma_f32_16x16x32_bf16 v[56:59], v[164:167], v[192:195], v[56:59]
	v_mfma_f32_16x16x32_bf16 v[52:55], v[184:187], v[192:195], v[52:55]
	v_mfma_f32_16x16x32_bf16 v[40:43], v[164:167], v[208:211], v[40:43]
	v_mfma_f32_16x16x32_bf16 v[36:39], v[184:187], v[208:211], v[36:39]
	v_mfma_f32_16x16x32_bf16 v[24:27], v[164:167], v[216:219], v[24:27]
	v_mfma_f32_16x16x32_bf16 v[20:23], v[184:187], v[216:219], v[20:23]
	v_mfma_f32_16x16x32_bf16 v[8:11], v[164:167], v[224:227], v[8:11]
	v_mfma_f32_16x16x32_bf16 v[4:7], v[184:187], v[224:227], v[4:7]
	v_mfma_f32_16x16x32_bf16 v[56:59], v[180:183], v[196:199], v[56:59]
	v_mfma_f32_16x16x32_bf16 v[52:55], v[188:191], v[196:199], v[52:55]
	v_mfma_f32_16x16x32_bf16 v[40:43], v[180:183], v[212:215], v[40:43]
	v_mfma_f32_16x16x32_bf16 v[36:39], v[188:191], v[212:215], v[36:39]
	v_mfma_f32_16x16x32_bf16 v[24:27], v[180:183], v[220:223], v[24:27]
	v_mfma_f32_16x16x32_bf16 v[20:23], v[188:191], v[220:223], v[20:23]
	v_mfma_f32_16x16x32_bf16 v[8:11], v[180:183], v[228:231], v[8:11]
	v_mfma_f32_16x16x32_bf16 v[4:7], v[188:191], v[228:231], v[4:7]
	s_barrier
	s_cbranch_scc0 .LBB0_1222
	s_and_b64 vcc, exec, s[8:9]
	s_cbranch_vccz .LBB0_1225
	s_barrier

.LBB0_1295:
	s_add_i32 s54, s24, 2
	s_add_u32 s25, s20, 0xffe00080
	s_addc_u32 s26, s21, -1
	s_add_i32 s55, 0, 0x10000
	s_cmp_eq_u32 s11, s24
	s_cselect_b32 s27, s13, s26
	s_cselect_b32 s26, s12, s25
	v_add_u32_e32 v2, s55, v1
	s_cselect_b32 s25, s19, s53
	s_cselect_b32 s24, s18, s17
	s_add_i32 s58, 0, 0x14000
	ds_read_b128 v[146:149], v2
	ds_read_b128 v[150:153], v2 offset:1024
	ds_read_b128 v[154:157], v2 offset:2048
	ds_read_b128 v[158:161], v2 offset:3072
	v_add_u32_e32 v2, s58, v1
	ds_read_b128 v[162:165], v2
	ds_read_b128 v[180:183], v2 offset:1024
	ds_read_b128 v[184:187], v2 offset:2048
	ds_read_b128 v[188:191], v2 offset:3072
	v_lshl_add_u64 v[166:167], s[20:21], 0, v[140:141]
	s_add_i32 m0, s40, 0xc000
	ds_read_b128 v[192:195], v145
	ds_read_b128 v[196:199], v145 offset:1024
	ds_read_b128 v[208:211], v145 offset:2048
	ds_read_b128 v[212:215], v145 offset:3072
	ds_read_b128 v[216:219], v145 offset:4096
	ds_read_b128 v[220:223], v145 offset:5120
	ds_read_b128 v[224:227], v145 offset:6144
	ds_read_b128 v[228:231], v145 offset:7168
	global_load_lds_dwordx4 v[166:167], off
	v_lshl_add_u64 v[166:167], s[20:21], 0, v[142:143]
	s_add_i32 m0, s40, 0xe000
	s_nop 0
	global_load_lds_dwordx4 v[166:167], off
	s_waitcnt vmcnt(8)
	s_waitcnt lgkmcnt(0)
	s_barrier
	s_waitcnt lgkmcnt(0)
	v_mfma_f32_16x16x32_bf16 v[128:131], v[146:149], v[192:195], v[128:131]
	v_mfma_f32_16x16x32_bf16 v[124:127], v[154:157], v[192:195], v[124:127]
	v_mfma_f32_16x16x32_bf16 v[120:123], v[146:149], v[208:211], v[120:123]
	v_mfma_f32_16x16x32_bf16 v[112:115], v[154:157], v[208:211], v[112:115]
	v_mfma_f32_16x16x32_bf16 v[104:107], v[146:149], v[216:219], v[104:107]
	v_mfma_f32_16x16x32_bf16 v[96:99], v[154:157], v[216:219], v[96:99]
	v_mfma_f32_16x16x32_bf16 v[88:91], v[146:149], v[224:227], v[88:91]
	v_mfma_f32_16x16x32_bf16 v[80:83], v[154:157], v[224:227], v[80:83]
	v_mfma_f32_16x16x32_bf16 v[128:131], v[150:153], v[196:199], v[128:131]
	v_mfma_f32_16x16x32_bf16 v[124:127], v[158:161], v[196:199], v[124:127]
	v_mfma_f32_16x16x32_bf16 v[120:123], v[150:153], v[212:215], v[120:123]
	v_mfma_f32_16x16x32_bf16 v[112:115], v[158:161], v[212:215], v[112:115]
	v_mfma_f32_16x16x32_bf16 v[104:107], v[150:153], v[220:223], v[104:107]
	v_mfma_f32_16x16x32_bf16 v[96:99], v[158:161], v[220:223], v[96:99]
	v_mfma_f32_16x16x32_bf16 v[88:91], v[150:153], v[228:231], v[88:91]
	v_mfma_f32_16x16x32_bf16 v[80:83], v[158:161], v[228:231], v[80:83]
	v_mfma_f32_16x16x32_bf16 v[116:119], v[162:165], v[192:195], v[116:119]
	v_mfma_f32_16x16x32_bf16 v[108:111], v[184:187], v[192:195], v[108:111]
	v_mfma_f32_16x16x32_bf16 v[100:103], v[162:165], v[208:211], v[100:103]
	v_mfma_f32_16x16x32_bf16 v[92:95], v[184:187], v[208:211], v[92:95]
	v_mfma_f32_16x16x32_bf16 v[84:87], v[162:165], v[216:219], v[84:87]
	v_mfma_f32_16x16x32_bf16 v[76:79], v[184:187], v[216:219], v[76:79]
	v_mfma_f32_16x16x32_bf16 v[72:75], v[162:165], v[224:227], v[72:75]
	v_mfma_f32_16x16x32_bf16 v[68:71], v[184:187], v[224:227], v[68:71]
	v_mfma_f32_16x16x32_bf16 v[116:119], v[180:183], v[196:199], v[116:119]
	v_mfma_f32_16x16x32_bf16 v[108:111], v[188:191], v[196:199], v[108:111]
	v_mfma_f32_16x16x32_bf16 v[100:103], v[180:183], v[212:215], v[100:103]
	v_mfma_f32_16x16x32_bf16 v[92:95], v[188:191], v[212:215], v[92:95]
	v_mfma_f32_16x16x32_bf16 v[84:87], v[180:183], v[220:223], v[84:87]
	v_mfma_f32_16x16x32_bf16 v[76:79], v[188:191], v[220:223], v[76:79]
	v_mfma_f32_16x16x32_bf16 v[72:75], v[180:183], v[228:231], v[72:75]
	v_mfma_f32_16x16x32_bf16 v[68:71], v[188:191], v[228:231], v[68:71]
	s_barrier
	s_add_i32 s55, s55, s35
	v_lshl_add_u64 v[166:167], s[24:25], 0, v[136:137]
	s_mov_b32 m0, s55
	ds_read_b128 v[192:195], v145 offset:16384
	ds_read_b128 v[196:199], v145 offset:17408
	ds_read_b128 v[208:211], v145 offset:18432
	ds_read_b128 v[212:215], v145 offset:19456
	ds_read_b128 v[216:219], v145 offset:20480
	ds_read_b128 v[220:223], v145 offset:21504
	ds_read_b128 v[224:227], v145 offset:22528
	ds_read_b128 v[228:231], v145 offset:23552
	global_load_lds_dwordx4 v[166:167], off
	s_add_i32 m0, s55, 0x2000
	s_add_u32 s56, s24, 0x200000
	v_lshl_add_u64 v[232:233], s[24:25], 0, v[132:133]
	s_addc_u32 s57, s25, 0
	s_add_i32 s55, s58, s35
	global_load_lds_dwordx4 v[232:233], off
	v_lshl_add_u64 v[234:235], s[56:57], 0, v[136:137]
	s_mov_b32 m0, s55
	v_lshl_add_u64 v[236:237], s[26:27], 0, v[134:135]
	global_load_lds_dwordx4 v[234:235], off
	v_lshl_add_u64 v[234:235], s[56:57], 0, v[132:133]
	s_add_i32 m0, s55, 0x2000
	s_nop 0
	global_load_lds_dwordx4 v[234:235], off
	v_lshl_add_u64 v[234:235], s[26:27], 0, v[138:139]
	s_mov_b32 m0, s40
	s_nop 0
	global_load_lds_dwordx4 v[234:235], off
	s_mov_b32 m0, s41
	s_nop 0
	global_load_lds_dwordx4 v[236:237], off
	s_waitcnt vmcnt(8)
	s_waitcnt lgkmcnt(0)
	s_barrier
	s_waitcnt lgkmcnt(0)
	v_mfma_f32_16x16x32_bf16 v[64:67], v[146:149], v[192:195], v[64:67]
	v_mfma_f32_16x16x32_bf16 v[60:63], v[154:157], v[192:195], v[60:63]
	v_mfma_f32_16x16x32_bf16 v[56:59], v[146:149], v[208:211], v[56:59]
	v_mfma_f32_16x16x32_bf16 v[48:51], v[154:157], v[208:211], v[48:51]
	v_mfma_f32_16x16x32_bf16 v[40:43], v[146:149], v[216:219], v[40:43]
	v_mfma_f32_16x16x32_bf16 v[32:35], v[154:157], v[216:219], v[32:35]
	v_mfma_f32_16x16x32_bf16 v[24:27], v[146:149], v[224:227], v[24:27]
	v_mfma_f32_16x16x32_bf16 v[16:19], v[154:157], v[224:227], v[16:19]
	v_mfma_f32_16x16x32_bf16 v[64:67], v[150:153], v[196:199], v[64:67]
	v_mfma_f32_16x16x32_bf16 v[60:63], v[158:161], v[196:199], v[60:63]
	v_mfma_f32_16x16x32_bf16 v[56:59], v[150:153], v[212:215], v[56:59]
	v_mfma_f32_16x16x32_bf16 v[48:51], v[158:161], v[212:215], v[48:51]
	v_mfma_f32_16x16x32_bf16 v[40:43], v[150:153], v[220:223], v[40:43]
	v_mfma_f32_16x16x32_bf16 v[32:35], v[158:161], v[220:223], v[32:35]
	v_mfma_f32_16x16x32_bf16 v[24:27], v[150:153], v[228:231], v[24:27]
	v_mfma_f32_16x16x32_bf16 v[16:19], v[158:161], v[228:231], v[16:19]
	v_mfma_f32_16x16x32_bf16 v[52:55], v[162:165], v[192:195], v[52:55]
	v_mfma_f32_16x16x32_bf16 v[44:47], v[184:187], v[192:195], v[44:47]
	v_mfma_f32_16x16x32_bf16 v[36:39], v[162:165], v[208:211], v[36:39]
	v_mfma_f32_16x16x32_bf16 v[28:31], v[184:187], v[208:211], v[28:31]
	v_mfma_f32_16x16x32_bf16 v[20:23], v[162:165], v[216:219], v[20:23]
	v_mfma_f32_16x16x32_bf16 v[12:15], v[184:187], v[216:219], v[12:15]
	v_mfma_f32_16x16x32_bf16 v[8:11], v[162:165], v[224:227], v[8:11]
	v_mfma_f32_16x16x32_bf16 v[4:7], v[184:187], v[224:227], v[4:7]
	v_mfma_f32_16x16x32_bf16 v[52:55], v[180:183], v[196:199], v[52:55]
	v_mfma_f32_16x16x32_bf16 v[44:47], v[188:191], v[196:199], v[44:47]
	v_mfma_f32_16x16x32_bf16 v[36:39], v[180:183], v[212:215], v[36:39]
	v_mfma_f32_16x16x32_bf16 v[28:31], v[188:191], v[212:215], v[28:31]
	v_mfma_f32_16x16x32_bf16 v[20:23], v[180:183], v[220:223], v[20:23]
	v_mfma_f32_16x16x32_bf16 v[12:15], v[188:191], v[220:223], v[12:15]
	v_mfma_f32_16x16x32_bf16 v[8:11], v[180:183], v[228:231], v[8:11]
	v_mfma_f32_16x16x32_bf16 v[4:7], v[188:191], v[228:231], v[4:7]
	s_barrier
	s_add_i32 s55, 0, 0x18000
	v_add_u32_e32 v2, s55, v1
	s_add_i32 s56, 0, 0x1c000
	ds_read_b128 v[146:149], v2
	ds_read_b128 v[150:153], v2 offset:1024
	ds_read_b128 v[154:157], v2 offset:2048
	ds_read_b128 v[158:161], v2 offset:3072
	v_add_u32_e32 v2, s56, v1
	ds_read_b128 v[162:165], v2
	ds_read_b128 v[180:183], v2 offset:1024
	ds_read_b128 v[184:187], v2 offset:2048
	ds_read_b128 v[188:191], v2 offset:3072
	s_add_u32 s26, s26, 0x200000
	s_addc_u32 s27, s27, 0
	s_mov_b32 m0, s42
	v_lshl_add_u64 v[238:239], s[26:27], 0, v[138:139]
	ds_read_b128 v[192:195], v145 offset:32768
	ds_read_b128 v[196:199], v145 offset:33792
	ds_read_b128 v[208:211], v145 offset:34816
	ds_read_b128 v[212:215], v145 offset:35840
	ds_read_b128 v[216:219], v145 offset:36864
	ds_read_b128 v[220:223], v145 offset:37888
	ds_read_b128 v[224:227], v145 offset:38912
	ds_read_b128 v[228:231], v145 offset:39936
	global_load_lds_dwordx4 v[238:239], off
	v_lshl_add_u64 v[238:239], s[26:27], 0, v[134:135]
	s_mov_b32 m0, s43
	s_nop 0
	global_load_lds_dwordx4 v[238:239], off
	s_waitcnt vmcnt(8)
	s_waitcnt lgkmcnt(0)
	s_barrier
	s_waitcnt lgkmcnt(0)
	v_mfma_f32_16x16x32_bf16 v[128:131], v[146:149], v[192:195], v[128:131]
	v_mfma_f32_16x16x32_bf16 v[124:127], v[154:157], v[192:195], v[124:127]
	v_mfma_f32_16x16x32_bf16 v[120:123], v[146:149], v[208:211], v[120:123]
	v_mfma_f32_16x16x32_bf16 v[112:115], v[154:157], v[208:211], v[112:115]
	v_mfma_f32_16x16x32_bf16 v[104:107], v[146:149], v[216:219], v[104:107]
	v_mfma_f32_16x16x32_bf16 v[96:99], v[154:157], v[216:219], v[96:99]
	v_mfma_f32_16x16x32_bf16 v[88:91], v[146:149], v[224:227], v[88:91]
	v_mfma_f32_16x16x32_bf16 v[80:83], v[154:157], v[224:227], v[80:83]
	v_mfma_f32_16x16x32_bf16 v[128:131], v[150:153], v[196:199], v[128:131]
	v_mfma_f32_16x16x32_bf16 v[124:127], v[158:161], v[196:199], v[124:127]
	v_mfma_f32_16x16x32_bf16 v[120:123], v[150:153], v[212:215], v[120:123]
	v_mfma_f32_16x16x32_bf16 v[112:115], v[158:161], v[212:215], v[112:115]
	v_mfma_f32_16x16x32_bf16 v[104:107], v[150:153], v[220:223], v[104:107]
	v_mfma_f32_16x16x32_bf16 v[96:99], v[158:161], v[220:223], v[96:99]
	v_mfma_f32_16x16x32_bf16 v[88:91], v[150:153], v[228:231], v[88:91]
	v_mfma_f32_16x16x32_bf16 v[80:83], v[158:161], v[228:231], v[80:83]
	v_mfma_f32_16x16x32_bf16 v[116:119], v[162:165], v[192:195], v[116:119]
	v_mfma_f32_16x16x32_bf16 v[108:111], v[184:187], v[192:195], v[108:111]
	v_mfma_f32_16x16x32_bf16 v[100:103], v[162:165], v[208:211], v[100:103]
	v_mfma_f32_16x16x32_bf16 v[92:95], v[184:187], v[208:211], v[92:95]
	v_mfma_f32_16x16x32_bf16 v[84:87], v[162:165], v[216:219], v[84:87]
	v_mfma_f32_16x16x32_bf16 v[76:79], v[184:187], v[216:219], v[76:79]
	v_mfma_f32_16x16x32_bf16 v[72:75], v[162:165], v[224:227], v[72:75]
	v_mfma_f32_16x16x32_bf16 v[68:71], v[184:187], v[224:227], v[68:71]
	v_mfma_f32_16x16x32_bf16 v[116:119], v[180:183], v[196:199], v[116:119]
	v_mfma_f32_16x16x32_bf16 v[108:111], v[188:191], v[196:199], v[108:111]
	v_mfma_f32_16x16x32_bf16 v[100:103], v[180:183], v[212:215], v[100:103]
	v_mfma_f32_16x16x32_bf16 v[92:95], v[188:191], v[212:215], v[92:95]
	v_mfma_f32_16x16x32_bf16 v[84:87], v[180:183], v[220:223], v[84:87]
	v_mfma_f32_16x16x32_bf16 v[76:79], v[188:191], v[220:223], v[76:79]
	v_mfma_f32_16x16x32_bf16 v[72:75], v[180:183], v[228:231], v[72:75]
	v_mfma_f32_16x16x32_bf16 v[68:71], v[188:191], v[228:231], v[68:71]
	s_barrier
	s_add_i32 s26, s55, s35
	v_lshl_add_u64 v[166:167], v[166:167], 0, s[2:3]
	s_mov_b32 m0, s26
	ds_read_b128 v[192:195], v145 offset:49152
	ds_read_b128 v[196:199], v145 offset:50176
	ds_read_b128 v[208:211], v145 offset:51200
	ds_read_b128 v[212:215], v145 offset:52224
	ds_read_b128 v[216:219], v145 offset:53248
	ds_read_b128 v[220:223], v145 offset:54272
	ds_read_b128 v[224:227], v145 offset:55296
	ds_read_b128 v[228:231], v145 offset:56320
	global_load_lds_dwordx4 v[166:167], off
	s_add_i32 m0, s26, 0x2000
	s_add_u32 s24, s24, 0x200080
	v_lshl_add_u64 v[166:167], v[232:233], 0, s[2:3]
	s_addc_u32 s25, s25, 0
	s_add_i32 s26, s56, s35
	global_load_lds_dwordx4 v[166:167], off
	v_lshl_add_u64 v[166:167], s[24:25], 0, v[136:137]
	s_mov_b32 m0, s26
	s_nop 0
	global_load_lds_dwordx4 v[166:167], off
	v_lshl_add_u64 v[166:167], s[24:25], 0, v[132:133]
	s_add_i32 m0, s26, 0x2000
	s_nop 0
	global_load_lds_dwordx4 v[166:167], off
	v_lshl_add_u64 v[166:167], v[234:235], 0, s[2:3]
	s_mov_b32 m0, s44
	s_nop 0
	global_load_lds_dwordx4 v[166:167], off
	v_lshl_add_u64 v[166:167], v[236:237], 0, s[2:3]
	s_mov_b32 m0, s45
	s_nop 0
	global_load_lds_dwordx4 v[166:167], off
	s_add_u32 s20, s20, 0x100
	s_addc_u32 s21, s21, 0
	s_add_u32 s17, s17, 0x100
	s_addc_u32 s53, s53, 0
	s_cmp_ge_u32 s54, s51
	s_mov_b32 s24, s54
	s_waitcnt vmcnt(8)
	s_waitcnt lgkmcnt(0)
	s_barrier
	s_waitcnt lgkmcnt(0)
	v_mfma_f32_16x16x32_bf16 v[64:67], v[146:149], v[192:195], v[64:67]
	v_mfma_f32_16x16x32_bf16 v[60:63], v[154:157], v[192:195], v[60:63]
	v_mfma_f32_16x16x32_bf16 v[56:59], v[146:149], v[208:211], v[56:59]
	v_mfma_f32_16x16x32_bf16 v[48:51], v[154:157], v[208:211], v[48:51]
	v_mfma_f32_16x16x32_bf16 v[40:43], v[146:149], v[216:219], v[40:43]
	v_mfma_f32_16x16x32_bf16 v[32:35], v[154:157], v[216:219], v[32:35]
	v_mfma_f32_16x16x32_bf16 v[24:27], v[146:149], v[224:227], v[24:27]
	v_mfma_f32_16x16x32_bf16 v[16:19], v[154:157], v[224:227], v[16:19]
	v_mfma_f32_16x16x32_bf16 v[64:67], v[150:153], v[196:199], v[64:67]
	v_mfma_f32_16x16x32_bf16 v[60:63], v[158:161], v[196:199], v[60:63]
	v_mfma_f32_16x16x32_bf16 v[56:59], v[150:153], v[212:215], v[56:59]
	v_mfma_f32_16x16x32_bf16 v[48:51], v[158:161], v[212:215], v[48:51]
	v_mfma_f32_16x16x32_bf16 v[40:43], v[150:153], v[220:223], v[40:43]
	v_mfma_f32_16x16x32_bf16 v[32:35], v[158:161], v[220:223], v[32:35]
	v_mfma_f32_16x16x32_bf16 v[24:27], v[150:153], v[228:231], v[24:27]
	v_mfma_f32_16x16x32_bf16 v[16:19], v[158:161], v[228:231], v[16:19]
	v_mfma_f32_16x16x32_bf16 v[52:55], v[162:165], v[192:195], v[52:55]
	v_mfma_f32_16x16x32_bf16 v[44:47], v[184:187], v[192:195], v[44:47]
	v_mfma_f32_16x16x32_bf16 v[36:39], v[162:165], v[208:211], v[36:39]
	v_mfma_f32_16x16x32_bf16 v[28:31], v[184:187], v[208:211], v[28:31]
	v_mfma_f32_16x16x32_bf16 v[20:23], v[162:165], v[216:219], v[20:23]
	v_mfma_f32_16x16x32_bf16 v[12:15], v[184:187], v[216:219], v[12:15]
	v_mfma_f32_16x16x32_bf16 v[8:11], v[162:165], v[224:227], v[8:11]
	v_mfma_f32_16x16x32_bf16 v[4:7], v[184:187], v[224:227], v[4:7]
	v_mfma_f32_16x16x32_bf16 v[52:55], v[180:183], v[196:199], v[52:55]
	v_mfma_f32_16x16x32_bf16 v[44:47], v[188:191], v[196:199], v[44:47]
	v_mfma_f32_16x16x32_bf16 v[36:39], v[180:183], v[212:215], v[36:39]
	v_mfma_f32_16x16x32_bf16 v[28:31], v[188:191], v[212:215], v[28:31]
	v_mfma_f32_16x16x32_bf16 v[20:23], v[180:183], v[220:223], v[20:23]
	v_mfma_f32_16x16x32_bf16 v[12:15], v[188:191], v[220:223], v[12:15]
	v_mfma_f32_16x16x32_bf16 v[8:11], v[180:183], v[228:231], v[8:11]
	v_mfma_f32_16x16x32_bf16 v[4:7], v[188:191], v[228:231], v[4:7]
	s_barrier
	s_cbranch_scc0 .LBB0_1295
	s_and_b64 vcc, exec, s[8:9]
	s_cbranch_vccz .LBB0_1298
	s_barrier
